# attention unit epilogue: gate tile loaded with whole-row 16-byte loads before the exchange barrier and staged in the idle LDS stage, gated output written back to LDS and stored as whole rows (replaces
# speedup vs baseline: 1.0314x; 1.0251x over previous
; __device__ __forceinline__ void attn_unit(const PT& p, LAS unsigned char* lds, int tid, int lane, int wave, int b, int hd, int qb, float lam) {
;     ...
;                 const int d = db * 32 + 8 * qd + 4 * h; const unsigned off = tokq * 2048u + (unsigned)(hd * 128 + d);
;                 const u32x2 gg = *(const u32x2*)(Gb + off); const f32x4 sg = *(const f32x4*)(p.in[20] + d);
.LBB0_1106:
	s_andn2_b64 vcc, exec, s[60:61]
	s_cbranch_vccnz .Lfin_nopf
	v_or_b32_e32 v8, s91, v241
	v_and_b32_e32 v9, 31, v198
	v_lshlrev_b32_e32 v9, 11, v9
	v_sub_u32_e32 v8, v8, v9
	v_lshrrev_b32_e32 v10, 4, v198
	v_lshl_add_u32 v8, v10, 11, v8
	v_and_b32_e32 v11, 15, v198
	v_lshl_add_u32 v8, v11, 3, v8
	v_lshlrev_b32_e32 v14, 1, v8
	s_mov_b64 s[98:99], s[2:3]
	global_load_dwordx4 v[134:137], v14, s[98:99]
	s_add_u32 s98, s98, 0x4000
	s_addc_u32 s99, s99, 0
	global_load_dwordx4 v[138:141], v14, s[98:99]
	s_add_u32 s98, s98, 0x4000
	s_addc_u32 s99, s99, 0
	global_load_dwordx4 v[154:157], v14, s[98:99]
	s_add_u32 s98, s98, 0x4000
	s_addc_u32 s99, s99, 0
	global_load_dwordx4 v[158:161], v14, s[98:99]
	s_add_u32 s98, s98, 0x4000
	s_addc_u32 s99, s99, 0
	global_load_dwordx4 v[162:165], v14, s[98:99]
	s_add_u32 s98, s98, 0x4000
	s_addc_u32 s99, s99, 0
	global_load_dwordx4 v[166:169], v14, s[98:99]
	s_add_u32 s98, s98, 0x4000
	s_addc_u32 s99, s99, 0
	global_load_dwordx4 v[170:173], v14, s[98:99]
	s_add_u32 s98, s98, 0x4000
	s_addc_u32 s99, s99, 0
	global_load_dwordx4 v[174:177], v14, s[98:99]

; __device__ __forceinline__ void attn_unit(const PT& p, LAS unsigned char* lds, int tid, int lane, int wave, int b, int hd, int qb, float lam) {
;     ...
;         const float i1 = 1.f / lt; float ss = 0.f;
; #pragma unroll
;         for (int db = 0; db < 4; ++db)
; #pragma unroll
;             for (int i = 0; i < 16; ++i) { const float o = oT[db][i] * i1 - xch[(db * 16 + i) * 64 + lane]; oT[db][i] = o; ss += o * o; }
;         ss += __shfl_xor(ss, 32);
;         const float rn = rsqrtf(ss * (1.f / 128.f) + EPS) * (1.f - LAMBDA_INIT);
;     ...
;                 const int d = db * 32 + 8 * qd + 4 * h; const unsigned off = tokq * 2048u + (unsigned)(hd * 128 + d);
;                 const u32x2 gg = *(const u32x2*)(Gb + off); const f32x4 sg = *(const f32x4*)(p.in[20] + d);
.LBB0_1108:
	s_andn2_b64 vcc, exec, s[60:61]
	s_waitcnt lgkmcnt(0)
	s_barrier
	s_cbranch_vccnz .LBB0_1073
	v_div_scale_f32 v5, s[36:37], v4, v4, 1.0
	v_rcp_f32_e32 v6, v5
	v_div_scale_f32 v7, vcc, 1.0, v4, 1.0
	ds_read_b64 v[2:3], v233
	v_fma_f32 v130, -v5, v6, 1.0
	v_fmac_f32_e32 v6, v130, v6
	v_mul_f32_e32 v132, v7, v6
	v_fma_f32 v133, -v5, v132, v7
	v_fmac_f32_e32 v132, v133, v6
	v_fma_f32 v5, -v5, v132, v7
	v_div_fmas_f32 v5, v5, v6, v132
	v_div_fixup_f32 v5, v5, v4, 1.0
	ds_read2st64_b32 v[52:53], v0 offset1:1
	ds_read2st64_b32 v[54:55], v0 offset0:2 offset1:3
	ds_read2st64_b32 v[56:57], v0 offset0:4 offset1:5
	ds_read2st64_b32 v[58:59], v0 offset0:6 offset1:7
	ds_read2st64_b32 v[60:61], v0 offset0:8 offset1:9
	ds_read2st64_b32 v[62:63], v0 offset0:10 offset1:11
	ds_read2st64_b32 v[64:65], v0 offset0:12 offset1:13
	ds_read2st64_b32 v[142:143], v0 offset0:14 offset1:15
	ds_read2st64_b32 v[144:145], v0 offset0:16 offset1:17
	ds_read2st64_b32 v[146:147], v0 offset0:18 offset1:19
	ds_read2st64_b32 v[148:149], v0 offset0:20 offset1:21
	ds_read2st64_b32 v[150:151], v0 offset0:22 offset1:23
	ds_read2st64_b32 v[152:153], v0 offset0:24 offset1:25
	ds_read2st64_b32 v[8:9], v0 offset0:26 offset1:27
	ds_read2st64_b32 v[10:11], v0 offset0:28 offset1:29
	ds_read2st64_b32 v[12:13], v0 offset0:30 offset1:31
	s_bitcmp1_b32 s95, 0
	s_cselect_b32 s38, 0x11000, 0
	v_bfe_u32 v6, v196, 6, 2
	v_mul_u32_u24_e32 v6, 0x2200, v6
	v_add_u32_e32 v6, s38, v6
	v_lshrrev_b32_e32 v7, 4, v198
	v_mul_u32_u24_e32 v7, 0x110, v7
	v_and_b32_e32 v130, 15, v198
	v_lshl_add_u32 v15, v130, 4, v7
	v_add_u32_e32 v15, v15, v6
	v_and_b32_e32 v7, 31, v198
	v_mul_u32_u24_e32 v7, 0x110, v7
	v_lshl_add_u32 v7, v178, 1, v7
	v_add_u32_e32 v1, v7, v6
	s_waitcnt lgkmcnt(0)
	v_readfirstlane_b32 s36, v2
	v_readfirstlane_b32 s37, v3
	v_lshlrev_b32_e32 v130, 2, v178
	s_nop 4
	global_load_dwordx4 v[18:21], v130, s[36:37]
	global_load_dwordx4 v[22:25], v130, s[36:37] offset:32
	global_load_dwordx4 v[26:29], v130, s[36:37] offset:64
	global_load_dwordx4 v[30:33], v130, s[36:37] offset:96
	global_load_dwordx4 v[34:37], v130, s[36:37] offset:128
	global_load_dwordx4 v[38:41], v130, s[36:37] offset:160
	global_load_dwordx4 v[42:45], v130, s[36:37] offset:192
	global_load_dwordx4 v[46:49], v130, s[36:37] offset:224
	v_fma_f32 v114, v114, v5, -v52
	v_fma_f32 v115, v115, v5, -v53
	v_mul_f32_e32 v6, v114, v114
	v_mul_f32_e32 v7, v115, v115
	v_fma_f32 v116, v116, v5, -v54
	v_fma_f32 v117, v117, v5, -v55
	v_fmac_f32_e32 v6, v116, v116
	v_fmac_f32_e32 v7, v117, v117
	v_fma_f32 v118, v118, v5, -v56
	v_fma_f32 v119, v119, v5, -v57
	v_fmac_f32_e32 v6, v118, v118
	v_fmac_f32_e32 v7, v119, v119
	v_fma_f32 v120, v120, v5, -v58
	v_fma_f32 v121, v121, v5, -v59
	v_fmac_f32_e32 v6, v120, v120
	v_fmac_f32_e32 v7, v121, v121
	v_fma_f32 v122, v122, v5, -v60
	v_fma_f32 v123, v123, v5, -v61
	v_fmac_f32_e32 v6, v122, v122
	v_fmac_f32_e32 v7, v123, v123
	v_fma_f32 v124, v124, v5, -v62
	v_fma_f32 v125, v125, v5, -v63
	v_fmac_f32_e32 v6, v124, v124
	v_fmac_f32_e32 v7, v125, v125
	v_fma_f32 v126, v126, v5, -v64
	v_fma_f32 v127, v127, v5, -v65
	v_fmac_f32_e32 v6, v126, v126
	v_fmac_f32_e32 v7, v127, v127
	v_fma_f32 v128, v128, v5, -v142
	v_fma_f32 v129, v129, v5, -v143
	v_fmac_f32_e32 v6, v128, v128
	v_fmac_f32_e32 v7, v129, v129
	v_fma_f32 v98, v98, v5, -v144
	v_fma_f32 v99, v99, v5, -v145
	v_fmac_f32_e32 v6, v98, v98
	v_fmac_f32_e32 v7, v99, v99
	v_fma_f32 v100, v100, v5, -v146
	v_fma_f32 v101, v101, v5, -v147
	v_fmac_f32_e32 v6, v100, v100
	v_fmac_f32_e32 v7, v101, v101
	v_fma_f32 v102, v102, v5, -v148
	v_fma_f32 v103, v103, v5, -v149
	v_fmac_f32_e32 v6, v102, v102
	v_fmac_f32_e32 v7, v103, v103
	v_fma_f32 v104, v104, v5, -v150
	v_fma_f32 v105, v105, v5, -v151
	v_fmac_f32_e32 v6, v104, v104
	v_fmac_f32_e32 v7, v105, v105
	v_fma_f32 v106, v106, v5, -v152
	v_fma_f32 v107, v107, v5, -v153
	v_fmac_f32_e32 v6, v106, v106
	v_fmac_f32_e32 v7, v107, v107
	v_fma_f32 v108, v108, v5, -v8
	v_fma_f32 v109, v109, v5, -v9
	v_fmac_f32_e32 v6, v108, v108
	v_fmac_f32_e32 v7, v109, v109
	v_fma_f32 v110, v110, v5, -v10
	v_fma_f32 v111, v111, v5, -v11
	v_fmac_f32_e32 v6, v110, v110
	v_fmac_f32_e32 v7, v111, v111
	v_fma_f32 v112, v112, v5, -v12
	v_fma_f32 v113, v113, v5, -v13
	v_fmac_f32_e32 v6, v112, v112
	v_fmac_f32_e32 v7, v113, v113
	ds_read2st64_b32 v[52:53], v0 offset0:32 offset1:33
	ds_read2st64_b32 v[54:55], v0 offset0:34 offset1:35
	ds_read2st64_b32 v[56:57], v0 offset0:36 offset1:37
	ds_read2st64_b32 v[58:59], v0 offset0:38 offset1:39
	ds_read2st64_b32 v[60:61], v0 offset0:40 offset1:41
	ds_read2st64_b32 v[62:63], v0 offset0:42 offset1:43
	ds_read2st64_b32 v[64:65], v0 offset0:44 offset1:45
	ds_read2st64_b32 v[142:143], v0 offset0:46 offset1:47
	ds_read2st64_b32 v[144:145], v0 offset0:48 offset1:49
	ds_read2st64_b32 v[146:147], v0 offset0:50 offset1:51
	ds_read2st64_b32 v[148:149], v0 offset0:52 offset1:53
	ds_read2st64_b32 v[150:151], v0 offset0:54 offset1:55
	ds_read2st64_b32 v[152:153], v0 offset0:56 offset1:57
	ds_read2st64_b32 v[8:9], v0 offset0:58 offset1:59
	ds_read2st64_b32 v[10:11], v0 offset0:60 offset1:61
	ds_read2st64_b32 v[12:13], v0 offset0:62 offset1:63
	s_waitcnt vmcnt(15)
	ds_write_b128 v15, v[134:137]
	s_waitcnt vmcnt(14)
	ds_write_b128 v15, v[138:141] offset:1088
	s_waitcnt vmcnt(13)
	ds_write_b128 v15, v[154:157] offset:2176
	s_waitcnt vmcnt(12)
	ds_write_b128 v15, v[158:161] offset:3264
	s_waitcnt vmcnt(11)
	ds_write_b128 v15, v[162:165] offset:4352
	s_waitcnt vmcnt(10)
	ds_write_b128 v15, v[166:169] offset:5440
	s_waitcnt vmcnt(9)
	ds_write_b128 v15, v[170:173] offset:6528
	s_waitcnt vmcnt(8)
; __device__ __forceinline__ float bflo(unsigned u) { return __uint_as_float(u << 16); }
; __device__ __forceinline__ float bfhi(unsigned u) { return __uint_as_float(u & 0xffff0000u); }
; __device__ __forceinline__ void attn_unit(const PT& p, LAS unsigned char* lds, int tid, int lane, int wave, int b, int hd, int qb, float lam) {
;     ...
;             for (int i = 0; i < 16; ++i) { const float o = oT[db][i] * i1 - xch[(db * 16 + i) * 64 + lane]; oT[db][i] = o; ss += o * o; }
;         ss += __shfl_xor(ss, 32);
;         const float rn = rsqrtf(ss * (1.f / 128.f) + EPS) * (1.f - LAMBDA_INIT);
; #pragma unroll
;         for (int db = 0; db < 4; ++db)
; #pragma unroll
;             for (int qd = 0; qd < 4; ++qd) {
;                 const int d = db * 32 + 8 * qd + 4 * h; const unsigned off = tokq * 2048u + (unsigned)(hd * 128 + d);
;                 const u32x2 gg = *(const u32x2*)(Gb + off); const f32x4 sg = *(const f32x4*)(p.in[20] + d);
;                 u32x2 w; w.x = pk2(oT[db][4 * qd] * rn * sg.x * bflo(gg.x), oT[db][4 * qd + 1] * rn * sg.y * bfhi(gg.x));
;                 w.y = pk2(oT[db][4 * qd + 2] * rn * sg.z * bflo(gg.y), oT[db][4 * qd + 3] * rn * sg.w * bfhi(gg.y));
;                 *(u32x2*)(Ob + off) = w;
	ds_write_b128 v15, v[174:177] offset:7616
	global_load_dwordx4 v[134:137], v130, s[36:37] offset:256
	global_load_dwordx4 v[138:141], v130, s[36:37] offset:288
	global_load_dwordx4 v[154:157], v130, s[36:37] offset:320
	global_load_dwordx4 v[158:161], v130, s[36:37] offset:352
	global_load_dwordx4 v[162:165], v130, s[36:37] offset:384
	global_load_dwordx4 v[166:169], v130, s[36:37] offset:416
	global_load_dwordx4 v[170:173], v130, s[36:37] offset:448
	global_load_dwordx4 v[174:177], v130, s[36:37] offset:480
	s_waitcnt lgkmcnt(8)
	v_fma_f32 v82, v82, v5, -v52
	v_fma_f32 v83, v83, v5, -v53
	v_fmac_f32_e32 v6, v82, v82
	v_fmac_f32_e32 v7, v83, v83
	v_fma_f32 v84, v84, v5, -v54
	v_fma_f32 v85, v85, v5, -v55
	v_fmac_f32_e32 v6, v84, v84
	v_fmac_f32_e32 v7, v85, v85
	v_fma_f32 v86, v86, v5, -v56
	v_fma_f32 v87, v87, v5, -v57
	v_fmac_f32_e32 v6, v86, v86
	v_fmac_f32_e32 v7, v87, v87
	v_fma_f32 v88, v88, v5, -v58
	v_fma_f32 v89, v89, v5, -v59
	v_fmac_f32_e32 v6, v88, v88
	v_fmac_f32_e32 v7, v89, v89
	v_fma_f32 v90, v90, v5, -v60
	v_fma_f32 v91, v91, v5, -v61
	v_fmac_f32_e32 v6, v90, v90
	v_fmac_f32_e32 v7, v91, v91
	v_fma_f32 v92, v92, v5, -v62
	v_fma_f32 v93, v93, v5, -v63
	v_fmac_f32_e32 v6, v92, v92
	v_fmac_f32_e32 v7, v93, v93
	v_fma_f32 v94, v94, v5, -v64
	v_fma_f32 v95, v95, v5, -v65
	v_fmac_f32_e32 v6, v94, v94
	v_fmac_f32_e32 v7, v95, v95
	v_fma_f32 v96, v96, v5, -v142
	v_fma_f32 v97, v97, v5, -v143
	v_fmac_f32_e32 v6, v96, v96
	v_fmac_f32_e32 v7, v97, v97
	v_fma_f32 v66, v66, v5, -v144
	v_fma_f32 v67, v67, v5, -v145
	v_fmac_f32_e32 v6, v66, v66
	v_fmac_f32_e32 v7, v67, v67
	v_fma_f32 v68, v68, v5, -v146
	v_fma_f32 v69, v69, v5, -v147
	v_fmac_f32_e32 v6, v68, v68
	v_fmac_f32_e32 v7, v69, v69
	v_fma_f32 v70, v70, v5, -v148
	v_fma_f32 v71, v71, v5, -v149
	v_fmac_f32_e32 v6, v70, v70
	v_fmac_f32_e32 v7, v71, v71
	v_fma_f32 v72, v72, v5, -v150
	v_fma_f32 v73, v73, v5, -v151
	v_fmac_f32_e32 v6, v72, v72
	v_fmac_f32_e32 v7, v73, v73
	v_fma_f32 v74, v74, v5, -v152
	v_fma_f32 v75, v75, v5, -v153
	v_fmac_f32_e32 v6, v74, v74
	v_fmac_f32_e32 v7, v75, v75
	v_fma_f32 v76, v76, v5, -v8
	v_fma_f32 v77, v77, v5, -v9
	v_fmac_f32_e32 v6, v76, v76
	v_fmac_f32_e32 v7, v77, v77
	v_fma_f32 v78, v78, v5, -v10
	v_fma_f32 v79, v79, v5, -v11
	v_fmac_f32_e32 v6, v78, v78
	v_fmac_f32_e32 v7, v79, v79
	v_fma_f32 v80, v80, v5, -v12
	v_fma_f32 v81, v81, v5, -v13
	v_fmac_f32_e32 v6, v80, v80
	v_fmac_f32_e32 v7, v81, v81
	v_add_f32_e32 v6, v6, v7
	ds_bpermute_b32 v7, v197, v6
	s_mov_b32 s38, 0x800000
	s_waitcnt lgkmcnt(0)
	v_add_f32_e32 v6, v6, v7
	v_fmamk_f32 v6, v6, 0x3c000000, v234
	v_mul_f32_e32 v7, 0x4b800000, v6
	v_cmp_gt_f32_e32 vcc, s38, v6
	s_nop 1
	v_cndmask_b32_e32 v6, v6, v7, vcc
	v_rsq_f32_e32 v7, v6
	s_nop 0
	v_mul_f32_e32 v6, 0x45800000, v7
	v_cndmask_b32_e32 v6, v7, v6, vcc
	v_mul_f32_e32 v50, 0x3f24fd5c, v6
	ds_read_b64 v[52:53], v1
	ds_read_b64 v[54:55], v1 offset:16
	s_waitcnt vmcnt(15)
	v_mul_f32_e32 v56, v114, v50
	v_mul_f32_e32 v57, v115, v50
	v_mul_f32_e32 v58, v116, v50
	v_mul_f32_e32 v59, v117, v50
	v_mul_f32_e32 v56, v18, v56
	v_mul_f32_e32 v57, v19, v57
	v_mul_f32_e32 v58, v20, v58
	v_mul_f32_e32 v59, v21, v59
	s_waitcnt lgkmcnt(1)
	v_lshlrev_b32_e32 v60, 16, v52
	v_and_b32_e32 v61, 0xffff0000, v52
	v_lshlrev_b32_e32 v62, 16, v53
	v_and_b32_e32 v63, 0xffff0000, v53
	v_mul_f32_e32 v56, v56, v60
	v_mul_f32_e32 v57, v57, v61
	v_mul_f32_e32 v58, v58, v62
	v_mul_f32_e32 v59, v59, v63
	v_cvt_pk_bf16_f32 v52, v56, v57
	v_cvt_pk_bf16_f32 v53, v58, v59
	ds_write_b64 v1, v[52:53]
	ds_read_b64 v[52:53], v1 offset:32
	s_waitcnt vmcnt(14)
	v_mul_f32_e32 v56, v118, v50
	v_mul_f32_e32 v57, v119, v50
	v_mul_f32_e32 v58, v120, v50
	v_mul_f32_e32 v59, v121, v50
	v_mul_f32_e32 v56, v22, v56
	v_mul_f32_e32 v57, v23, v57
	v_mul_f32_e32 v58, v24, v58
	v_mul_f32_e32 v59, v25, v59
	s_waitcnt lgkmcnt(1)
	v_lshlrev_b32_e32 v60, 16, v54
	v_and_b32_e32 v61, 0xffff0000, v54
	v_lshlrev_b32_e32 v62, 16, v55
	v_and_b32_e32 v63, 0xffff0000, v55
	v_mul_f32_e32 v56, v56, v60
	v_mul_f32_e32 v57, v57, v61
	v_mul_f32_e32 v58, v58, v62
	v_mul_f32_e32 v59, v59, v63
	v_cvt_pk_bf16_f32 v54, v56, v57
	v_cvt_pk_bf16_f32 v55, v58, v59
	ds_write_b64 v1, v[54:55] offset:16
	ds_read_b64 v[54:55], v1 offset:48
	s_waitcnt vmcnt(13)
	v_mul_f32_e32 v56, v122, v50
	v_mul_f32_e32 v57, v123, v50
	v_mul_f32_e32 v58, v124, v50
	v_mul_f32_e32 v59, v125, v50
	v_mul_f32_e32 v56, v26, v56
	v_mul_f32_e32 v57, v27, v57
	v_mul_f32_e32 v58, v28, v58
	v_mul_f32_e32 v59, v29, v59
	s_waitcnt lgkmcnt(1)
	v_lshlrev_b32_e32 v60, 16, v52
	v_and_b32_e32 v61, 0xffff0000, v52
	v_lshlrev_b32_e32 v62, 16, v53
	v_and_b32_e32 v63, 0xffff0000, v53
	v_mul_f32_e32 v56, v56, v60
	v_mul_f32_e32 v57, v57, v61
	v_mul_f32_e32 v58, v58, v62
	v_mul_f32_e32 v59, v59, v63
	v_cvt_pk_bf16_f32 v52, v56, v57
	v_cvt_pk_bf16_f32 v53, v58, v59
	ds_write_b64 v1, v[52:53] offset:32
	ds_read_b64 v[52:53], v1 offset:64
	s_waitcnt vmcnt(12)
	v_mul_f32_e32 v56, v126, v50
	v_mul_f32_e32 v57, v127, v50
	v_mul_f32_e32 v58, v128, v50
	v_mul_f32_e32 v59, v129, v50
	v_mul_f32_e32 v56, v30, v56
	v_mul_f32_e32 v57, v31, v57
	v_mul_f32_e32 v58, v32, v58
	v_mul_f32_e32 v59, v33, v59
	s_waitcnt lgkmcnt(1)
	v_lshlrev_b32_e32 v60, 16, v54
	v_and_b32_e32 v61, 0xffff0000, v54
	v_lshlrev_b32_e32 v62, 16, v55
	v_and_b32_e32 v63, 0xffff0000, v55
	v_mul_f32_e32 v56, v56, v60
	v_mul_f32_e32 v57, v57, v61
	v_mul_f32_e32 v58, v58, v62
	v_mul_f32_e32 v59, v59, v63
	v_cvt_pk_bf16_f32 v54, v56, v57
	v_cvt_pk_bf16_f32 v55, v58, v59
	ds_write_b64 v1, v[54:55] offset:48
	ds_read_b64 v[54:55], v1 offset:80
	s_waitcnt vmcnt(11)
; __device__ __forceinline__ float bflo(unsigned u) { return __uint_as_float(u << 16); }
; __device__ __forceinline__ float bfhi(unsigned u) { return __uint_as_float(u & 0xffff0000u); }
; __device__ __forceinline__ void attn_unit(const PT& p, LAS unsigned char* lds, int tid, int lane, int wave, int b, int hd, int qb, float lam) {
;     ...
;         for (int db = 0; db < 4; ++db)
; #pragma unroll
;             for (int qd = 0; qd < 4; ++qd) {
;                 const int d = db * 32 + 8 * qd + 4 * h; const unsigned off = tokq * 2048u + (unsigned)(hd * 128 + d);
;                 const u32x2 gg = *(const u32x2*)(Gb + off); const f32x4 sg = *(const f32x4*)(p.in[20] + d);
;                 u32x2 w; w.x = pk2(oT[db][4 * qd] * rn * sg.x * bflo(gg.x), oT[db][4 * qd + 1] * rn * sg.y * bfhi(gg.x));
;                 w.y = pk2(oT[db][4 * qd + 2] * rn * sg.z * bflo(gg.y), oT[db][4 * qd + 3] * rn * sg.w * bfhi(gg.y));
;                 *(u32x2*)(Ob + off) = w;
	v_mul_f32_e32 v56, v98, v50
	v_mul_f32_e32 v57, v99, v50
	v_mul_f32_e32 v58, v100, v50
	v_mul_f32_e32 v59, v101, v50
	v_mul_f32_e32 v56, v34, v56
	v_mul_f32_e32 v57, v35, v57
	v_mul_f32_e32 v58, v36, v58
	v_mul_f32_e32 v59, v37, v59
	s_waitcnt lgkmcnt(1)
	v_lshlrev_b32_e32 v60, 16, v52
	v_and_b32_e32 v61, 0xffff0000, v52
	v_lshlrev_b32_e32 v62, 16, v53
	v_and_b32_e32 v63, 0xffff0000, v53
	v_mul_f32_e32 v56, v56, v60
	v_mul_f32_e32 v57, v57, v61
	v_mul_f32_e32 v58, v58, v62
	v_mul_f32_e32 v59, v59, v63
	v_cvt_pk_bf16_f32 v52, v56, v57
	v_cvt_pk_bf16_f32 v53, v58, v59
	ds_write_b64 v1, v[52:53] offset:64
	ds_read_b64 v[52:53], v1 offset:96
	s_waitcnt vmcnt(10)
	v_mul_f32_e32 v56, v102, v50
	v_mul_f32_e32 v57, v103, v50
	v_mul_f32_e32 v58, v104, v50
	v_mul_f32_e32 v59, v105, v50
	v_mul_f32_e32 v56, v38, v56
	v_mul_f32_e32 v57, v39, v57
	v_mul_f32_e32 v58, v40, v58
	v_mul_f32_e32 v59, v41, v59
	s_waitcnt lgkmcnt(1)
	v_lshlrev_b32_e32 v60, 16, v54
	v_and_b32_e32 v61, 0xffff0000, v54
	v_lshlrev_b32_e32 v62, 16, v55
	v_and_b32_e32 v63, 0xffff0000, v55
	v_mul_f32_e32 v56, v56, v60
	v_mul_f32_e32 v57, v57, v61
	v_mul_f32_e32 v58, v58, v62
	v_mul_f32_e32 v59, v59, v63
	v_cvt_pk_bf16_f32 v54, v56, v57
	v_cvt_pk_bf16_f32 v55, v58, v59
	ds_write_b64 v1, v[54:55] offset:80
	ds_read_b64 v[54:55], v1 offset:112
	s_waitcnt vmcnt(9)
	v_mul_f32_e32 v56, v106, v50
	v_mul_f32_e32 v57, v107, v50
	v_mul_f32_e32 v58, v108, v50
	v_mul_f32_e32 v59, v109, v50
	v_mul_f32_e32 v56, v42, v56
	v_mul_f32_e32 v57, v43, v57
	v_mul_f32_e32 v58, v44, v58
	v_mul_f32_e32 v59, v45, v59
	s_waitcnt lgkmcnt(1)
	v_lshlrev_b32_e32 v60, 16, v52
	v_and_b32_e32 v61, 0xffff0000, v52
	v_lshlrev_b32_e32 v62, 16, v53
	v_and_b32_e32 v63, 0xffff0000, v53
	v_mul_f32_e32 v56, v56, v60
	v_mul_f32_e32 v57, v57, v61
	v_mul_f32_e32 v58, v58, v62
	v_mul_f32_e32 v59, v59, v63
	v_cvt_pk_bf16_f32 v52, v56, v57
	v_cvt_pk_bf16_f32 v53, v58, v59
	ds_write_b64 v1, v[52:53] offset:96
	ds_read_b64 v[52:53], v1 offset:128
	s_waitcnt vmcnt(8)
	v_mul_f32_e32 v56, v110, v50
	v_mul_f32_e32 v57, v111, v50
	v_mul_f32_e32 v58, v112, v50
	v_mul_f32_e32 v59, v113, v50
	v_mul_f32_e32 v56, v46, v56
	v_mul_f32_e32 v57, v47, v57
	v_mul_f32_e32 v58, v48, v58
	v_mul_f32_e32 v59, v49, v59
	s_waitcnt lgkmcnt(1)
	v_lshlrev_b32_e32 v60, 16, v54
	v_and_b32_e32 v61, 0xffff0000, v54
	v_lshlrev_b32_e32 v62, 16, v55
	v_and_b32_e32 v63, 0xffff0000, v55
	v_mul_f32_e32 v56, v56, v60
	v_mul_f32_e32 v57, v57, v61
	v_mul_f32_e32 v58, v58, v62
	v_mul_f32_e32 v59, v59, v63
	v_cvt_pk_bf16_f32 v54, v56, v57
	v_cvt_pk_bf16_f32 v55, v58, v59
	ds_write_b64 v1, v[54:55] offset:112
	ds_read_b64 v[54:55], v1 offset:144
	s_waitcnt vmcnt(7)
	v_mul_f32_e32 v56, v82, v50
	v_mul_f32_e32 v57, v83, v50
	v_mul_f32_e32 v58, v84, v50
	v_mul_f32_e32 v59, v85, v50
	v_mul_f32_e32 v56, v134, v56
	v_mul_f32_e32 v57, v135, v57
	v_mul_f32_e32 v58, v136, v58
	v_mul_f32_e32 v59, v137, v59
	s_waitcnt lgkmcnt(1)
	v_lshlrev_b32_e32 v60, 16, v52
	v_and_b32_e32 v61, 0xffff0000, v52
	v_lshlrev_b32_e32 v62, 16, v53
	v_and_b32_e32 v63, 0xffff0000, v53
	v_mul_f32_e32 v56, v56, v60
	v_mul_f32_e32 v57, v57, v61
	v_mul_f32_e32 v58, v58, v62
	v_mul_f32_e32 v59, v59, v63
	v_cvt_pk_bf16_f32 v52, v56, v57
	v_cvt_pk_bf16_f32 v53, v58, v59
	ds_write_b64 v1, v[52:53] offset:128
	ds_read_b64 v[52:53], v1 offset:160
	s_waitcnt vmcnt(6)
	v_mul_f32_e32 v56, v86, v50
	v_mul_f32_e32 v57, v87, v50
	v_mul_f32_e32 v58, v88, v50
	v_mul_f32_e32 v59, v89, v50
	v_mul_f32_e32 v56, v138, v56
	v_mul_f32_e32 v57, v139, v57
	v_mul_f32_e32 v58, v140, v58
	v_mul_f32_e32 v59, v141, v59
	s_waitcnt lgkmcnt(1)
	v_lshlrev_b32_e32 v60, 16, v54
	v_and_b32_e32 v61, 0xffff0000, v54
	v_lshlrev_b32_e32 v62, 16, v55
	v_and_b32_e32 v63, 0xffff0000, v55
	v_mul_f32_e32 v56, v56, v60
	v_mul_f32_e32 v57, v57, v61
	v_mul_f32_e32 v58, v58, v62
	v_mul_f32_e32 v59, v59, v63
	v_cvt_pk_bf16_f32 v54, v56, v57
	v_cvt_pk_bf16_f32 v55, v58, v59
	ds_write_b64 v1, v[54:55] offset:144
	ds_read_b64 v[54:55], v1 offset:176
	s_waitcnt vmcnt(5)
	v_mul_f32_e32 v56, v90, v50
	v_mul_f32_e32 v57, v91, v50
	v_mul_f32_e32 v58, v92, v50
	v_mul_f32_e32 v59, v93, v50
	v_mul_f32_e32 v56, v154, v56
	v_mul_f32_e32 v57, v155, v57
	v_mul_f32_e32 v58, v156, v58
	v_mul_f32_e32 v59, v157, v59
	s_waitcnt lgkmcnt(1)
	v_lshlrev_b32_e32 v60, 16, v52
	v_and_b32_e32 v61, 0xffff0000, v52
	v_lshlrev_b32_e32 v62, 16, v53
	v_and_b32_e32 v63, 0xffff0000, v53
	v_mul_f32_e32 v56, v56, v60
	v_mul_f32_e32 v57, v57, v61
	v_mul_f32_e32 v58, v58, v62
	v_mul_f32_e32 v59, v59, v63
	v_cvt_pk_bf16_f32 v52, v56, v57
	v_cvt_pk_bf16_f32 v53, v58, v59
	ds_write_b64 v1, v[52:53] offset:160
	ds_read_b64 v[52:53], v1 offset:192
	s_waitcnt vmcnt(4)
; __device__ __forceinline__ float bflo(unsigned u) { return __uint_as_float(u << 16); }
; __device__ __forceinline__ float bfhi(unsigned u) { return __uint_as_float(u & 0xffff0000u); }
; __device__ __forceinline__ void attn_unit(const PT& p, LAS unsigned char* lds, int tid, int lane, int wave, int b, int hd, int qb, float lam) {
;     ...
;         for (int db = 0; db < 4; ++db)
; #pragma unroll
;             for (int qd = 0; qd < 4; ++qd) {
;                 const int d = db * 32 + 8 * qd + 4 * h; const unsigned off = tokq * 2048u + (unsigned)(hd * 128 + d);
;                 const u32x2 gg = *(const u32x2*)(Gb + off); const f32x4 sg = *(const f32x4*)(p.in[20] + d);
;                 u32x2 w; w.x = pk2(oT[db][4 * qd] * rn * sg.x * bflo(gg.x), oT[db][4 * qd + 1] * rn * sg.y * bfhi(gg.x));
;                 w.y = pk2(oT[db][4 * qd + 2] * rn * sg.z * bflo(gg.y), oT[db][4 * qd + 3] * rn * sg.w * bfhi(gg.y));
;                 *(u32x2*)(Ob + off) = w;
	v_mul_f32_e32 v56, v94, v50
	v_mul_f32_e32 v57, v95, v50
	v_mul_f32_e32 v58, v96, v50
	v_mul_f32_e32 v59, v97, v50
	v_mul_f32_e32 v56, v158, v56
	v_mul_f32_e32 v57, v159, v57
	v_mul_f32_e32 v58, v160, v58
	v_mul_f32_e32 v59, v161, v59
	s_waitcnt lgkmcnt(1)
	v_lshlrev_b32_e32 v60, 16, v54
	v_and_b32_e32 v61, 0xffff0000, v54
	v_lshlrev_b32_e32 v62, 16, v55
	v_and_b32_e32 v63, 0xffff0000, v55
	v_mul_f32_e32 v56, v56, v60
	v_mul_f32_e32 v57, v57, v61
	v_mul_f32_e32 v58, v58, v62
	v_mul_f32_e32 v59, v59, v63
	v_cvt_pk_bf16_f32 v54, v56, v57
	v_cvt_pk_bf16_f32 v55, v58, v59
	ds_write_b64 v1, v[54:55] offset:176
	ds_read_b64 v[54:55], v1 offset:208
	s_waitcnt vmcnt(3)
	v_mul_f32_e32 v56, v66, v50
	v_mul_f32_e32 v57, v67, v50
	v_mul_f32_e32 v58, v68, v50
	v_mul_f32_e32 v59, v69, v50
	v_mul_f32_e32 v56, v162, v56
	v_mul_f32_e32 v57, v163, v57
	v_mul_f32_e32 v58, v164, v58
	v_mul_f32_e32 v59, v165, v59
	s_waitcnt lgkmcnt(1)
	v_lshlrev_b32_e32 v60, 16, v52
	v_and_b32_e32 v61, 0xffff0000, v52
	v_lshlrev_b32_e32 v62, 16, v53
	v_and_b32_e32 v63, 0xffff0000, v53
	v_mul_f32_e32 v56, v56, v60
	v_mul_f32_e32 v57, v57, v61
	v_mul_f32_e32 v58, v58, v62
	v_mul_f32_e32 v59, v59, v63
	v_cvt_pk_bf16_f32 v52, v56, v57
	v_cvt_pk_bf16_f32 v53, v58, v59
	ds_write_b64 v1, v[52:53] offset:192
	ds_read_b64 v[52:53], v1 offset:224
	s_waitcnt vmcnt(2)
	v_mul_f32_e32 v56, v70, v50
	v_mul_f32_e32 v57, v71, v50
	v_mul_f32_e32 v58, v72, v50
	v_mul_f32_e32 v59, v73, v50
	v_mul_f32_e32 v56, v166, v56
	v_mul_f32_e32 v57, v167, v57
	v_mul_f32_e32 v58, v168, v58
	v_mul_f32_e32 v59, v169, v59
	s_waitcnt lgkmcnt(1)
	v_lshlrev_b32_e32 v60, 16, v54
	v_and_b32_e32 v61, 0xffff0000, v54
	v_lshlrev_b32_e32 v62, 16, v55
	v_and_b32_e32 v63, 0xffff0000, v55
	v_mul_f32_e32 v56, v56, v60
	v_mul_f32_e32 v57, v57, v61
	v_mul_f32_e32 v58, v58, v62
	v_mul_f32_e32 v59, v59, v63
	v_cvt_pk_bf16_f32 v54, v56, v57
	v_cvt_pk_bf16_f32 v55, v58, v59
	ds_write_b64 v1, v[54:55] offset:208
	ds_read_b64 v[54:55], v1 offset:240
	s_waitcnt vmcnt(1)
	v_mul_f32_e32 v56, v74, v50
	v_mul_f32_e32 v57, v75, v50
	v_mul_f32_e32 v58, v76, v50
	v_mul_f32_e32 v59, v77, v50
	v_mul_f32_e32 v56, v170, v56
	v_mul_f32_e32 v57, v171, v57
	v_mul_f32_e32 v58, v172, v58
	v_mul_f32_e32 v59, v173, v59
	s_waitcnt lgkmcnt(1)
	v_lshlrev_b32_e32 v60, 16, v52
	v_and_b32_e32 v61, 0xffff0000, v52
	v_lshlrev_b32_e32 v62, 16, v53
	v_and_b32_e32 v63, 0xffff0000, v53
	v_mul_f32_e32 v56, v56, v60
	v_mul_f32_e32 v57, v57, v61
	v_mul_f32_e32 v58, v58, v62
	v_mul_f32_e32 v59, v59, v63
	v_cvt_pk_bf16_f32 v52, v56, v57
	v_cvt_pk_bf16_f32 v53, v58, v59
	ds_write_b64 v1, v[52:53] offset:224
	s_waitcnt vmcnt(0)
	v_mul_f32_e32 v56, v78, v50
	v_mul_f32_e32 v57, v79, v50
	v_mul_f32_e32 v58, v80, v50
	v_mul_f32_e32 v59, v81, v50
	v_mul_f32_e32 v56, v174, v56
	v_mul_f32_e32 v57, v175, v57
	v_mul_f32_e32 v58, v176, v58
	v_mul_f32_e32 v59, v177, v59
	s_waitcnt lgkmcnt(0)
	v_lshlrev_b32_e32 v60, 16, v54
	v_and_b32_e32 v61, 0xffff0000, v54
	v_lshlrev_b32_e32 v62, 16, v55
	v_and_b32_e32 v63, 0xffff0000, v55
	v_mul_f32_e32 v56, v56, v60
	v_mul_f32_e32 v57, v57, v61
	v_mul_f32_e32 v58, v58, v62
	v_mul_f32_e32 v59, v59, v63
	v_cvt_pk_bf16_f32 v54, v56, v57
	v_cvt_pk_bf16_f32 v55, v58, v59
	ds_write_b64 v1, v[54:55] offset:240
	s_waitcnt lgkmcnt(0)
	ds_read_b128 v[18:21], v15
	ds_read_b128 v[22:25], v15 offset:1088
	ds_read_b128 v[26:29], v15 offset:2176
	ds_read_b128 v[30:33], v15 offset:3264
	ds_read_b128 v[34:37], v15 offset:4352
	ds_read_b128 v[38:41], v15 offset:5440
	ds_read_b128 v[42:45], v15 offset:6528
	ds_read_b128 v[46:49], v15 offset:7616
	s_mov_b64 s[98:99], s[44:45]
	s_waitcnt lgkmcnt(7)
	global_store_dwordx4 v14, v[18:21], s[98:99]
	s_add_u32 s98, s98, 0x4000
	s_addc_u32 s99, s99, 0
	s_waitcnt lgkmcnt(6)
	global_store_dwordx4 v14, v[22:25], s[98:99]
	s_add_u32 s98, s98, 0x4000
	s_addc_u32 s99, s99, 0
	s_waitcnt lgkmcnt(5)
	global_store_dwordx4 v14, v[26:29], s[98:99]
	s_add_u32 s98, s98, 0x4000
	s_addc_u32 s99, s99, 0
	s_waitcnt lgkmcnt(4)
	global_store_dwordx4 v14, v[30:33], s[98:99]
	s_add_u32 s98, s98, 0x4000
	s_addc_u32 s99, s99, 0
	s_waitcnt lgkmcnt(3)
	global_store_dwordx4 v14, v[34:37], s[98:99]
	s_add_u32 s98, s98, 0x4000
	s_addc_u32 s99, s99, 0
	s_waitcnt lgkmcnt(2)
	global_store_dwordx4 v14, v[38:41], s[98:99]
	s_add_u32 s98, s98, 0x4000
	s_addc_u32 s99, s99, 0
	s_waitcnt lgkmcnt(1)
	global_store_dwordx4 v14, v[42:45], s[98:99]
	s_add_u32 s98, s98, 0x4000
	s_addc_u32 s99, s99, 0
	s_waitcnt lgkmcnt(0)
	global_store_dwordx4 v14, v[46:49], s[98:99]
	s_branch .LBB0_1073
